# v39 + layer-0 XB conversion loop de-serialised: 8 row-chunk loads issued together with counted waits (was load-wait-store per chunk)
# speedup vs baseline: 1.0184x; 1.0011x over previous
; __device__ __forceinline__ unsigned pk2(float lo, float hi) { const f32v2_t v = {lo, hi}; const bf16v2_t b = __builtin_convertvector(v, bf16v2_t); return __builtin_bit_cast(unsigned, b); }
; __device__ __forceinline__ void phase_prep(const Args& a, int l, unsigned char* lds, int G) {
;     ...
;         for (int row = gw; row < T; row += NGW) {
;             const f32x4* xr = (const f32x4*)(x + (size_t)row * DM) + lane; u32x2* o = (u32x2*)(XB + (size_t)row * DM) + lane;
;             float ss = 0.f;
; #pragma unroll
;             for (int i = 0; i < 8; ++i) { const f32x4 v = xr[64 * i]; ss += v[0] * v[0] + v[1] * v[1] + v[2] * v[2] + v[3] * v[3]; u32x2 w; w.x = pk2(v[0], v[1]); w.y = pk2(v[2], v[3]); o[64 * i] = w; }
;             ss = wave_sum(ss);
;             if (lane == 0) rss[row] = (unsigned long long)(ss * 16777216.f);
;         }
.LBB0_1064:
	s_waitcnt lgkmcnt(0)
	global_load_dwordx4 v[14:17], v[4:5], off offset:-4096
	global_load_dwordx4 v[18:21], v[4:5], off offset:-3072
	global_load_dwordx4 v[22:25], v[4:5], off offset:-2048
	global_load_dwordx4 v[26:29], v[4:5], off offset:-1024
	global_load_dwordx4 v[30:33], v[4:5], off
	global_load_dwordx4 v[34:37], v[4:5], off offset:1024
	global_load_dwordx4 v[38:41], v[4:5], off offset:2048
	global_load_dwordx4 v[42:45], v[4:5], off offset:3072
	v_lshl_add_u64 v[58:59], s[82:83], 0, v[6:7]
	v_add_co_u32_e32 v46, vcc, s11, v58
	s_nop 1
	v_addc_co_u32_e32 v47, vcc, 0, v59, vcc
	s_waitcnt vmcnt(7)
	v_cvt_pk_bf16_f32 v56, v14, v15
	v_cvt_pk_bf16_f32 v57, v16, v17
	global_store_dwordx2 v[46:47], v[56:57], off
	v_mul_f32_e32 v15, v15, v15
	v_fmac_f32_e32 v15, v14, v14
	v_fmac_f32_e32 v15, v16, v16
	v_fmac_f32_e32 v15, v17, v17
	s_waitcnt vmcnt(7)
	v_cvt_pk_bf16_f32 v60, v18, v19
	v_cvt_pk_bf16_f32 v61, v20, v21
	global_store_dwordx2 v[46:47], v[60:61], off offset:512
	v_mul_f32_e32 v14, v19, v19
	v_fmac_f32_e32 v14, v18, v18
	v_fmac_f32_e32 v14, v20, v20
	v_fmac_f32_e32 v14, v21, v21
	v_add_f32_e32 v14, v15, v14
	s_waitcnt vmcnt(7)
	v_cvt_pk_bf16_f32 v56, v22, v23
	v_cvt_pk_bf16_f32 v57, v24, v25
	global_store_dwordx2 v[46:47], v[56:57], off offset:1024
	v_mul_f32_e32 v15, v23, v23
	v_fmac_f32_e32 v15, v22, v22
	v_fmac_f32_e32 v15, v24, v24
	v_fmac_f32_e32 v15, v25, v25
	v_add_f32_e32 v14, v14, v15
	s_waitcnt vmcnt(7)
	v_cvt_pk_bf16_f32 v60, v26, v27
	v_cvt_pk_bf16_f32 v61, v28, v29
	global_store_dwordx2 v[46:47], v[60:61], off offset:1536
	v_mul_f32_e32 v15, v27, v27
	v_fmac_f32_e32 v15, v26, v26
	v_fmac_f32_e32 v15, v28, v28
	v_fmac_f32_e32 v15, v29, v29
	v_add_f32_e32 v14, v14, v15
	s_waitcnt vmcnt(7)
	v_cvt_pk_bf16_f32 v56, v30, v31
	v_cvt_pk_bf16_f32 v57, v32, v33
	global_store_dwordx2 v[46:47], v[56:57], off offset:2048
	v_mul_f32_e32 v15, v31, v31
	v_fmac_f32_e32 v15, v30, v30
	v_fmac_f32_e32 v15, v32, v32
	v_fmac_f32_e32 v15, v33, v33
	v_add_f32_e32 v14, v14, v15
	s_waitcnt vmcnt(7)
	v_cvt_pk_bf16_f32 v60, v34, v35
	v_cvt_pk_bf16_f32 v61, v36, v37
	global_store_dwordx2 v[46:47], v[60:61], off offset:2560
	v_mul_f32_e32 v15, v35, v35
	v_fmac_f32_e32 v15, v34, v34
	v_fmac_f32_e32 v15, v36, v36
	v_fmac_f32_e32 v15, v37, v37
	v_add_f32_e32 v14, v14, v15
	s_waitcnt vmcnt(7)
	v_cvt_pk_bf16_f32 v56, v38, v39
	v_cvt_pk_bf16_f32 v57, v40, v41
	global_store_dwordx2 v[46:47], v[56:57], off offset:3072
	v_mul_f32_e32 v15, v39, v39
	v_fmac_f32_e32 v15, v38, v38
	v_fmac_f32_e32 v15, v40, v40
	v_fmac_f32_e32 v15, v41, v41
	v_add_f32_e32 v14, v14, v15
	s_waitcnt vmcnt(7)
	v_cvt_pk_bf16_f32 v60, v42, v43
	v_cvt_pk_bf16_f32 v61, v44, v45
	global_store_dwordx2 v[46:47], v[60:61], off offset:3584
	v_mul_f32_e32 v15, v43, v43
	v_fmac_f32_e32 v15, v42, v42
	v_fmac_f32_e32 v15, v44, v44
	v_fmac_f32_e32 v15, v45, v45
	v_add_f32_e32 v14, v14, v15
	ds_bpermute_b32 v15, v1, v14
	s_waitcnt lgkmcnt(0)
	v_add_f32_e32 v14, v14, v15
	ds_bpermute_b32 v15, v8, v14
	s_waitcnt lgkmcnt(0)
	v_add_f32_e32 v14, v14, v15
	ds_bpermute_b32 v15, v9, v14
	s_waitcnt lgkmcnt(0)
	v_add_f32_e32 v14, v14, v15
	ds_bpermute_b32 v15, v10, v14
	s_waitcnt lgkmcnt(0)
	v_add_f32_e32 v14, v14, v15
	ds_bpermute_b32 v15, v11, v14
	s_waitcnt lgkmcnt(0)
	v_add_f32_e32 v14, v14, v15
	ds_bpermute_b32 v15, v12, v14
	s_and_saveexec_b64 s[40:41], s[0:1]
	s_cbranch_execz .LBB0_1063
	s_waitcnt lgkmcnt(0)
	v_add_f32_e32 v14, v14, v15
	v_mul_f32_e32 v14, 0x4b800000, v14
	v_trunc_f32_e32 v14, v14
	v_mul_f32_e32 v15, 0x2f800000, v14
	v_floor_f32_e32 v15, v15
	v_fmac_f32_e32 v14, 0xcf800000, v15
	v_cvt_u32_f32_e32 v14, v14
	v_cvt_u32_f32_e32 v15, v15
	v_lshl_add_u64 v[16:17], s[82:83], 0, v[2:3]
	global_store_dwordx2 v[16:17], v[14:15], off
	s_branch .LBB0_1063
